# grid barrier: released workgroups poll the cross-XCC generation word directly (one release hop less)
# speedup vs baseline: 1.0022x; 1.0019x over previous
; DI unsigned xb_ld(unsigned* p) { return __hip_atomic_load(p, __ATOMIC_RELAXED, __HIP_MEMORY_SCOPE_AGENT); }
; DI unsigned xb_add(unsigned* p, unsigned v) { return __hip_atomic_fetch_add(p, v, __ATOMIC_RELAXED, __HIP_MEMORY_SCOPE_AGENT); }
; #define XB_SPIN(cond, bar) do { unsigned _sp = 0; while (cond) { __builtin_amdgcn_s_sleep(1); \
;     if ((++_sp & 255u) == 0u) { if (xb_ld(&(bar)[XB_TMO])) break; if (_sp > XB_SPIN_CAP) { atomicAdd(&(bar)[XB_TMO], 1u); break; } } } } while (0)
; DI void xcd_barrier(const XcdBarrier& b) {
;     ...
;     const unsigned old = xb_add(&bar[XB_XSUB(b.x)], 1u);
;     const unsigned gen = old / nloc;
;     if (old + 1u == (gen + 1u) * nloc) {
;       __builtin_amdgcn_fence(__ATOMIC_RELEASE, "agent");
;       asm volatile("s_waitcnt vmcnt(0)" ::: "memory");
;       const unsigned og = xb_add(&bar[XB_TOP], 1u);
;       const unsigned tg = og / nx;
;       if (og + 1u == (tg + 1u) * nx) xb_add(&bar[XB_TOPGEN], 1u);
;       else XB_SPIN(xb_ld(&bar[XB_TOPGEN]) == tg, bar);
;       __builtin_amdgcn_fence(__ATOMIC_ACQUIRE, "agent");
;       xb_add(&bar[XB_XGEN(b.x)], 1u);
;       asm volatile("s_waitcnt vmcnt(0)" ::: "memory");
;     } else {
;       XB_SPIN(xb_ld(&bar[XB_XGEN(b.x)]) == gen, bar);
.LBB0_113:
	s_or_b64 exec, exec, s[8:9]
	v_cvt_f32_u32_e32 v4, v2
	s_waitcnt vmcnt(0)
	v_readfirstlane_b32 s6, v3
	v_sub_u32_e32 v3, 0, v2
	v_rcp_iflag_f32_e32 v4, v4
	v_add_u32_e32 v5, s6, v1
	v_mul_f32_e32 v4, 0x4f7ffffe, v4
	v_cvt_u32_f32_e32 v4, v4
	v_mul_lo_u32 v1, v3, v4
	v_mul_hi_u32 v1, v4, v1
	v_add_u32_e32 v1, v4, v1
	v_mul_hi_u32 v1, v5, v1
	v_mul_lo_u32 v3, v1, v2
	v_sub_u32_e32 v3, v5, v3
	v_add_u32_e32 v4, 1, v1
	v_sub_u32_e32 v6, v3, v2
	v_cmp_ge_u32_e32 vcc, v3, v2
	s_nop 1
	v_cndmask_b32_e32 v1, v1, v4, vcc
	v_cndmask_b32_e32 v3, v3, v6, vcc
	v_add_u32_e32 v4, 1, v1
	v_cmp_ge_u32_e32 vcc, v3, v2
	v_add_u32_e32 v3, 1, v5
	s_nop 0
	v_cndmask_b32_e32 v1, v1, v4, vcc
	v_mul_lo_u32 v4, v2, v1
	v_add_u32_e32 v2, v4, v2
	v_cmp_ne_u32_e32 vcc, v3, v2
	s_and_saveexec_b64 s[6:7], vcc
	s_xor_b64 s[6:7], exec, s[6:7]
	s_cbranch_execz .LBB0_127
	s_waitcnt lgkmcnt(0)
	v_readlane_b32 s10, v253, 22
	v_readlane_b32 s11, v253, 23
	s_nop 4
	global_load_dword v0, v161, s[10:11] sc1
	s_waitcnt vmcnt(0)
	v_cmp_eq_u32_e32 vcc, v0, v1
	s_and_saveexec_b64 s[8:9], vcc
	s_cbranch_execz .LBB0_126
	s_mov_b32 s22, 1
	s_mov_b64 s[12:13], 0
	s_branch .LBB0_117

; DI unsigned xb_ld(unsigned* p) { return __hip_atomic_load(p, __ATOMIC_RELAXED, __HIP_MEMORY_SCOPE_AGENT); }
; DI unsigned xb_add(unsigned* p, unsigned v) { return __hip_atomic_fetch_add(p, v, __ATOMIC_RELAXED, __HIP_MEMORY_SCOPE_AGENT); }
; #define XB_SPIN(cond, bar) do { unsigned _sp = 0; while (cond) { __builtin_amdgcn_s_sleep(1); \
;     if ((++_sp & 255u) == 0u) { if (xb_ld(&(bar)[XB_TMO])) break; if (_sp > XB_SPIN_CAP) { atomicAdd(&(bar)[XB_TMO], 1u); break; } } } } while (0)
; DI void xcd_barrier(const XcdBarrier& b) {
;     ...
;     const unsigned old = xb_add(&bar[XB_XSUB(b.x)], 1u);
;     const unsigned gen = old / nloc;
;     if (old + 1u == (gen + 1u) * nloc) {
;       __builtin_amdgcn_fence(__ATOMIC_RELEASE, "agent");
;       asm volatile("s_waitcnt vmcnt(0)" ::: "memory");
;       const unsigned og = xb_add(&bar[XB_TOP], 1u);
;       const unsigned tg = og / nx;
;       if (og + 1u == (tg + 1u) * nx) xb_add(&bar[XB_TOPGEN], 1u);
;       else XB_SPIN(xb_ld(&bar[XB_TOPGEN]) == tg, bar);
;       __builtin_amdgcn_fence(__ATOMIC_ACQUIRE, "agent");
;       xb_add(&bar[XB_XGEN(b.x)], 1u);
;       asm volatile("s_waitcnt vmcnt(0)" ::: "memory");
;     } else {
;       XB_SPIN(xb_ld(&bar[XB_XGEN(b.x)]) == gen, bar);
.LBB0_199:
	s_or_b64 exec, exec, s[10:11]
	v_cvt_f32_u32_e32 v4, v2
	s_waitcnt vmcnt(0)
	v_readfirstlane_b32 s2, v3
	v_sub_u32_e32 v3, 0, v2
	v_rcp_iflag_f32_e32 v4, v4
	v_add_u32_e32 v5, s2, v1
	v_mul_f32_e32 v4, 0x4f7ffffe, v4
	v_cvt_u32_f32_e32 v4, v4
	v_mul_lo_u32 v1, v3, v4
	v_mul_hi_u32 v1, v4, v1
	v_add_u32_e32 v1, v4, v1
	v_mul_hi_u32 v1, v5, v1
	v_mul_lo_u32 v3, v1, v2
	v_sub_u32_e32 v3, v5, v3
	v_add_u32_e32 v4, 1, v1
	v_cmp_ge_u32_e32 vcc, v3, v2
	s_nop 1
	v_cndmask_b32_e32 v1, v1, v4, vcc
	v_sub_u32_e32 v4, v3, v2
	v_cndmask_b32_e32 v3, v3, v4, vcc
	v_add_u32_e32 v4, 1, v1
	v_cmp_ge_u32_e32 vcc, v3, v2
	v_add_u32_e32 v3, 1, v5
	s_nop 0
	v_cndmask_b32_e32 v1, v1, v4, vcc
	v_mul_lo_u32 v4, v2, v1
	v_add_u32_e32 v2, v4, v2
	v_cmp_ne_u32_e32 vcc, v3, v2
	s_and_saveexec_b64 s[6:7], vcc
	s_xor_b64 s[6:7], exec, s[6:7]
	s_cbranch_execz .LBB0_213
	s_waitcnt lgkmcnt(0)
	v_readlane_b32 s14, v253, 22
	v_readlane_b32 s15, v253, 23
	s_nop 4
	global_load_dword v0, v161, s[14:15] sc1
	s_waitcnt vmcnt(0)
	v_cmp_eq_u32_e32 vcc, v0, v1
	s_and_saveexec_b64 s[10:11], vcc
	s_cbranch_execz .LBB0_212
	s_mov_b32 s2, 1
	s_mov_b64 s[16:17], 0
	s_branch .LBB0_203

; DI unsigned xb_ld(unsigned* p) { return __hip_atomic_load(p, __ATOMIC_RELAXED, __HIP_MEMORY_SCOPE_AGENT); }
; DI unsigned xb_add(unsigned* p, unsigned v) { return __hip_atomic_fetch_add(p, v, __ATOMIC_RELAXED, __HIP_MEMORY_SCOPE_AGENT); }
; #define XB_SPIN(cond, bar) do { unsigned _sp = 0; while (cond) { __builtin_amdgcn_s_sleep(1); \
;     if ((++_sp & 255u) == 0u) { if (xb_ld(&(bar)[XB_TMO])) break; if (_sp > XB_SPIN_CAP) { atomicAdd(&(bar)[XB_TMO], 1u); break; } } } } while (0)
; DI void xcd_barrier(const XcdBarrier& b) {
;     ...
;     const unsigned old = xb_add(&bar[XB_XSUB(b.x)], 1u);
;     const unsigned gen = old / nloc;
;     if (old + 1u == (gen + 1u) * nloc) {
;       __builtin_amdgcn_fence(__ATOMIC_RELEASE, "agent");
;       asm volatile("s_waitcnt vmcnt(0)" ::: "memory");
;       const unsigned og = xb_add(&bar[XB_TOP], 1u);
;       const unsigned tg = og / nx;
;       if (og + 1u == (tg + 1u) * nx) xb_add(&bar[XB_TOPGEN], 1u);
;       else XB_SPIN(xb_ld(&bar[XB_TOPGEN]) == tg, bar);
;       __builtin_amdgcn_fence(__ATOMIC_ACQUIRE, "agent");
;       xb_add(&bar[XB_XGEN(b.x)], 1u);
;       asm volatile("s_waitcnt vmcnt(0)" ::: "memory");
;     } else {
;       XB_SPIN(xb_ld(&bar[XB_XGEN(b.x)]) == gen, bar);
.LBB0_375:
	s_or_b64 exec, exec, s[8:9]
	v_cvt_f32_u32_e32 v4, v2
	s_waitcnt vmcnt(0)
	v_readfirstlane_b32 s2, v3
	v_sub_u32_e32 v3, 0, v2
	v_rcp_iflag_f32_e32 v4, v4
	v_add_u32_e32 v5, s2, v1
	v_mul_f32_e32 v4, 0x4f7ffffe, v4
	v_cvt_u32_f32_e32 v4, v4
	v_mul_lo_u32 v1, v3, v4
	v_mul_hi_u32 v1, v4, v1
	v_add_u32_e32 v1, v4, v1
	v_mul_hi_u32 v1, v5, v1
	v_mul_lo_u32 v3, v1, v2
	v_sub_u32_e32 v3, v5, v3
	v_add_u32_e32 v4, 1, v1
	v_cmp_ge_u32_e32 vcc, v3, v2
	s_nop 1
	v_cndmask_b32_e32 v1, v1, v4, vcc
	v_sub_u32_e32 v4, v3, v2
	v_cndmask_b32_e32 v3, v3, v4, vcc
	v_add_u32_e32 v4, 1, v1
	v_cmp_ge_u32_e32 vcc, v3, v2
	v_add_u32_e32 v3, 1, v5
	s_nop 0
	v_cndmask_b32_e32 v1, v1, v4, vcc
	v_mul_lo_u32 v4, v2, v1
	v_add_u32_e32 v2, v4, v2
	v_cmp_ne_u32_e32 vcc, v3, v2
	s_and_saveexec_b64 s[6:7], vcc
	s_xor_b64 s[6:7], exec, s[6:7]
	s_cbranch_execz .LBB0_389
	s_waitcnt lgkmcnt(0)
	v_readlane_b32 s10, v253, 22
	v_readlane_b32 s11, v253, 23
	s_nop 4
	global_load_dword v0, v161, s[10:11] sc1
	s_waitcnt vmcnt(0)
	v_cmp_eq_u32_e32 vcc, v0, v1
	s_and_saveexec_b64 s[8:9], vcc
	s_cbranch_execz .LBB0_388
	s_mov_b32 s2, 1
	s_mov_b64 s[16:17], 0
	s_branch .LBB0_379

; DI unsigned xb_ld(unsigned* p) { return __hip_atomic_load(p, __ATOMIC_RELAXED, __HIP_MEMORY_SCOPE_AGENT); }
; DI unsigned xb_add(unsigned* p, unsigned v) { return __hip_atomic_fetch_add(p, v, __ATOMIC_RELAXED, __HIP_MEMORY_SCOPE_AGENT); }
; #define XB_SPIN(cond, bar) do { unsigned _sp = 0; while (cond) { __builtin_amdgcn_s_sleep(1); \
;     if ((++_sp & 255u) == 0u) { if (xb_ld(&(bar)[XB_TMO])) break; if (_sp > XB_SPIN_CAP) { atomicAdd(&(bar)[XB_TMO], 1u); break; } } } } while (0)
; DI void xcd_barrier(const XcdBarrier& b) {
;     ...
;     const unsigned old = xb_add(&bar[XB_XSUB(b.x)], 1u);
;     const unsigned gen = old / nloc;
;     if (old + 1u == (gen + 1u) * nloc) {
;       __builtin_amdgcn_fence(__ATOMIC_RELEASE, "agent");
;       asm volatile("s_waitcnt vmcnt(0)" ::: "memory");
;       const unsigned og = xb_add(&bar[XB_TOP], 1u);
;       const unsigned tg = og / nx;
;       if (og + 1u == (tg + 1u) * nx) xb_add(&bar[XB_TOPGEN], 1u);
;       else XB_SPIN(xb_ld(&bar[XB_TOPGEN]) == tg, bar);
;       __builtin_amdgcn_fence(__ATOMIC_ACQUIRE, "agent");
;       xb_add(&bar[XB_XGEN(b.x)], 1u);
;       asm volatile("s_waitcnt vmcnt(0)" ::: "memory");
;     } else {
;       XB_SPIN(xb_ld(&bar[XB_XGEN(b.x)]) == gen, bar);
.LBB0_654:
	s_or_b64 exec, exec, s[8:9]
	v_cvt_f32_u32_e32 v4, v2
	s_waitcnt vmcnt(0)
	v_readfirstlane_b32 s2, v3
	v_sub_u32_e32 v3, 0, v2
	v_rcp_iflag_f32_e32 v4, v4
	v_add_u32_e32 v5, s2, v1
	v_mul_f32_e32 v4, 0x4f7ffffe, v4
	v_cvt_u32_f32_e32 v4, v4
	v_mul_lo_u32 v1, v3, v4
	v_mul_hi_u32 v1, v4, v1
	v_add_u32_e32 v1, v4, v1
	v_mul_hi_u32 v1, v5, v1
	v_mul_lo_u32 v3, v1, v2
	v_sub_u32_e32 v3, v5, v3
	v_add_u32_e32 v4, 1, v1
	v_cmp_ge_u32_e32 vcc, v3, v2
	s_nop 1
	v_cndmask_b32_e32 v1, v1, v4, vcc
	v_sub_u32_e32 v4, v3, v2
	v_cndmask_b32_e32 v3, v3, v4, vcc
	v_add_u32_e32 v4, 1, v1
	v_cmp_ge_u32_e32 vcc, v3, v2
	v_add_u32_e32 v3, 1, v5
	s_nop 0
	v_cndmask_b32_e32 v1, v1, v4, vcc
	v_mul_lo_u32 v4, v2, v1
	v_add_u32_e32 v2, v4, v2
	v_cmp_ne_u32_e32 vcc, v3, v2
	s_and_saveexec_b64 s[6:7], vcc
	s_xor_b64 s[6:7], exec, s[6:7]
	s_cbranch_execz .LBB0_668
	s_waitcnt lgkmcnt(0)
	v_readlane_b32 s10, v253, 22
	v_readlane_b32 s11, v253, 23
	s_nop 4
	global_load_dword v0, v161, s[10:11] sc1
	s_waitcnt vmcnt(0)
	v_cmp_eq_u32_e32 vcc, v0, v1
	s_and_saveexec_b64 s[8:9], vcc
	s_cbranch_execz .LBB0_667
	s_mov_b32 s2, 1
	s_mov_b64 s[12:13], 0
	s_branch .LBB0_658
